# dropped the now-redundant vmcnt(0) drains between the residual epilogue and the sample GEMM
# speedup vs baseline: 1.0642x; 1.0000x over previous
; #define LAS __attribute__((address_space(3)))
; template <bool GATE>
; __device__ __forceinline__ void sample_gemm_res(LAS unsigned char* lds, const bf16* Amat, const bf16* Bt, const bf16* Hin, bf16* Hout, float* rss_out, const bf16* PP, const float* rss_in, int bid, int tid) {
;     const int wave = tid >> 6, lane = tid & 63, lr = lane & 15, kg = lane >> 4;
;   for (int tile = bid; tile < 256; tile += (int)gridDim.x) {
.LBB0_61:
	v_readlane_b32 s72, v254, 15
	s_cmpk_gt_u32 s13, 0xff
	v_readlane_b32 s71, v254, 14
	v_readlane_b32 s73, v254, 16
	v_mov_b32_e32 v222, v224
	v_mov_b32_e32 v225, 0x990
	v_mov_b32_e32 v226, 0xaa0
	v_mov_b32_e32 v227, 0xbb0
	s_cbranch_scc1 .LBB0_63

; template <bool GATE>
; __device__ __forceinline__ void sample_gemm_res(LAS unsigned char* lds, const bf16* Amat, const bf16* Bt, const bf16* Hin, bf16* Hout, float* rss_out, const bf16* PP, const float* rss_in, int bid, int tid) {
;     const int wave = tid >> 6, lane = tid & 63, lr = lane & 15, kg = lane >> 4;
;   for (int tile = bid; tile < 256; tile += (int)gridDim.x) {
;     const int m0 = TP + (tile & 7) * 64, n0 = (tile >> 3) * 64;
;     const bf16x8* ap = (const bf16x8*)(Amat + (size_t)(m0 + lr) * 2048 + wave * 256 + 8 * kg);
;     const bf16x8* bp = (const bf16x8*)(Bt + (size_t)(n0 + lr) * 2048 + wave * 256 + 8 * kg);
;     const int erow = m0 + (tid >> 3); const size_t ep = (size_t)erow * 2048 + n0 + (tid & 7) * 8;
;     const u32x4 hw = *(const u32x4*)(Hin + ep); u32x4 pw = (u32x4){0u, 0u, 0u, 0u}; float rsi = 0.f; if (GATE) { pw = *(const u32x4*)(PP + ep); rsi = rss_in[erow]; }
;     ...
;       sq += __shfl_xor(sq, 1); sq += __shfl_xor(sq, 2); sq += __shfl_xor(sq, 4);
.LBB0_64:
	v_mov_b32_e32 v0, v183
	s_and_b64 vcc, exec, s[40:41]
	s_cbranch_vccnz .LBB0_71
	v_and_b32_e32 v8, 64, v216
	v_xor_b32_e32 v7, 1, v216
	v_add_u32_e32 v8, 64, v8
	v_cmp_lt_i32_e32 vcc, v7, v8
	v_and_b32_e32 v75, 15, v0
	v_bfe_u32 v4, v0, 4, 2
	v_cndmask_b32_e32 v7, v216, v7, vcc
	v_lshlrev_b32_e32 v90, 2, v7
	v_xor_b32_e32 v7, 2, v216
	v_lshlrev_b32_e32 v2, 2, v0
	v_ashrrev_i32_e32 v88, 3, v0
	v_and_b32_e32 v5, 7, v0
	v_and_b32_e32 v0, 0x3fffffc0, v0
	v_cmp_lt_i32_e32 vcc, v7, v8
	v_lshl_or_b32 v0, v4, 2, v0
	s_load_dwordx2 s[0:1], s[60:61], 0x148
	v_cndmask_b32_e32 v7, v216, v7, vcc
	v_and_b32_e32 v2, 0xffffff00, v2
	v_lshlrev_b32_e32 v6, 2, v75
	v_lshlrev_b32_e32 v91, 2, v7
	v_xor_b32_e32 v7, 4, v216
	v_mul_lo_u32 v0, v0, s30
	s_waitcnt lgkmcnt(0)
	v_ashrrev_i32_e32 v3, 31, v2
	v_cmp_lt_i32_e32 vcc, v7, v8
	v_add3_u32 v93, 0, v6, v0
	v_lshlrev_b32_e32 v0, 4, v4
	v_lshlrev_b32_e32 v74, 3, v5
	v_lshl_add_u32 v89, v5, 5, 0
	v_cndmask_b32_e32 v7, v216, v7, vcc
	v_cmp_eq_u32_e32 vcc, 0, v5
	v_mul_lo_u32 v94, v88, s30
	v_lshl_add_u64 v[4:5], s[56:57], 0, v[0:1]
	v_lshlrev_b64 v[2:3], 1, v[2:3]
	v_lshlrev_b32_e32 v92, 2, v7
	v_add_u32_e32 v6, 0x10400, v94
	v_add_u32_e32 v7, 0x14500, v94
	v_add_u32_e32 v8, 0x18600, v94
	v_add_u32_e32 v9, 0x1c700, v94
	v_lshl_add_u64 v[4:5], v[4:5], 0, v[2:3]
	v_or_b32_e32 v2, v2, v0
	v_readlane_b32 s6, v254, 39
	v_lshl_add_u64 v[76:77], s[0:1], 0, v[4:5]
	v_lshl_add_u64 v[78:79], s[0:1], 0, v[2:3]
	v_or_b32_e32 v95, 0x2000, v75
	s_lshl_b32 s2, s6, 6
	v_add_u32_e32 v96, v89, v6
	v_add_u32_e32 v97, v89, v7
	v_add_u32_e32 v98, v89, v8
	v_add_u32_e32 v99, v89, v9
	s_mov_b32 s3, s59
	s_cmpk_lg_i32 s92, 0x100
	s_cbranch_scc1 .Lsmp_map_keep67
	s_and_b32 s4, s6, 7
	s_lshr_b32 s5, s6, 3
	s_lshl_b32 s4, s4, 2
	s_lshr_b32 s2, s5, 3
	s_add_i32 s4, s4, s2
	s_and_b32 s5, s5, 7
	s_lshl_b32 s4, s4, 3
	s_or_b32 s6, s4, s5
	s_lshl_b32 s2, s6, 6
	s_lshl_b32 s3, s6, 3

; #define LAS __attribute__((address_space(3)))
; template <bool GATE>
; __device__ __forceinline__ void sample_gemm_res(LAS unsigned char* lds, const bf16* Amat, const bf16* Bt, const bf16* Hin, bf16* Hout, float* rss_out, const bf16* PP, const float* rss_in, int bid, int tid) {
;     const int wave = tid >> 6, lane = tid & 63, lr = lane & 15, kg = lane >> 4;
;   for (int tile = bid; tile < 256; tile += (int)gridDim.x) {
.LBB0_109:
	v_readlane_b32 s72, v254, 15
	s_cmpk_gt_u32 s13, 0xff
	v_readlane_b32 s71, v254, 14
	v_readlane_b32 s73, v254, 16
	s_mov_b32 s39, s59
	s_mov_b32 s62, s64
	s_cbranch_scc1 .LBB0_111

; template <bool GATE>
; __device__ __forceinline__ void sample_gemm_res(LAS unsigned char* lds, const bf16* Amat, const bf16* Bt, const bf16* Hin, bf16* Hout, float* rss_out, const bf16* PP, const float* rss_in, int bid, int tid) {
;     const int wave = tid >> 6, lane = tid & 63, lr = lane & 15, kg = lane >> 4;
;   for (int tile = bid; tile < 256; tile += (int)gridDim.x) {
;     const int m0 = TP + (tile & 7) * 64, n0 = (tile >> 3) * 64;
;     const bf16x8* ap = (const bf16x8*)(Amat + (size_t)(m0 + lr) * 2048 + wave * 256 + 8 * kg);
;     const bf16x8* bp = (const bf16x8*)(Bt + (size_t)(n0 + lr) * 2048 + wave * 256 + 8 * kg);
;     const int erow = m0 + (tid >> 3); const size_t ep = (size_t)erow * 2048 + n0 + (tid & 7) * 8;
;     const u32x4 hw = *(const u32x4*)(Hin + ep); u32x4 pw = (u32x4){0u, 0u, 0u, 0u}; float rsi = 0.f; if (GATE) { pw = *(const u32x4*)(PP + ep); rsi = rss_in[erow]; }
;     ...
;       sq += __shfl_xor(sq, 1); sq += __shfl_xor(sq, 2); sq += __shfl_xor(sq, 4);
.LBB0_112:
	v_mov_b32_e32 v0, v183
	s_and_b64 vcc, exec, s[40:41]
	s_cbranch_vccnz .LBB0_119
	v_and_b32_e32 v8, 64, v216
	v_xor_b32_e32 v7, 1, v216
	v_add_u32_e32 v8, 64, v8
	v_cmp_lt_i32_e32 vcc, v7, v8
	v_and_b32_e32 v71, 15, v0
	v_bfe_u32 v4, v0, 4, 2
	v_cndmask_b32_e32 v7, v216, v7, vcc
	v_lshlrev_b32_e32 v86, 2, v7
	v_xor_b32_e32 v7, 2, v216
	v_lshlrev_b32_e32 v2, 2, v0
	v_ashrrev_i32_e32 v84, 3, v0
	v_and_b32_e32 v5, 7, v0
	v_and_b32_e32 v0, 0x3fffffc0, v0
	v_cmp_lt_i32_e32 vcc, v7, v8
	v_lshl_or_b32 v0, v4, 2, v0
	v_lshlrev_b32_e32 v6, 2, v71
	v_cndmask_b32_e32 v7, v216, v7, vcc
	v_lshlrev_b32_e32 v87, 2, v7
	v_xor_b32_e32 v7, 4, v216
	v_mul_lo_u32 v0, v0, s30
	s_add_u32 s0, s14, s52
	v_cmp_lt_i32_e32 vcc, v7, v8
	v_add3_u32 v89, 0, v6, v0
	s_addc_u32 s1, 0, s53
	v_lshlrev_b32_e32 v0, 4, v4
	v_lshlrev_b32_e32 v70, 3, v5
	v_lshl_add_u32 v85, v5, 5, 0
	v_cndmask_b32_e32 v7, v216, v7, vcc
	v_cmp_eq_u32_e32 vcc, 0, v5
	v_lshl_add_u64 v[4:5], s[0:1], 0, v[0:1]
	s_load_dwordx2 s[0:1], s[60:61], 0x148
	v_and_b32_e32 v2, 0xffffff00, v2
	s_waitcnt lgkmcnt(0)
	v_ashrrev_i32_e32 v3, 31, v2
	v_mul_lo_u32 v90, v84, s30
	v_lshlrev_b64 v[2:3], 1, v[2:3]
	v_lshlrev_b32_e32 v88, 2, v7
	v_add_u32_e32 v6, 0x10400, v90
	v_add_u32_e32 v7, 0x14500, v90
	v_add_u32_e32 v8, 0x18600, v90
	v_add_u32_e32 v9, 0x1c700, v90
	v_lshl_add_u64 v[4:5], v[4:5], 0, v[2:3]
	v_or_b32_e32 v2, v2, v0
	v_readlane_b32 s6, v254, 39
	v_lshl_add_u64 v[72:73], s[0:1], 0, v[4:5]
	v_lshl_add_u64 v[74:75], s[0:1], 0, v[2:3]
	v_or_b32_e32 v91, 0x2000, v71
	s_lshl_b32 s2, s6, 6
	v_add_u32_e32 v92, v85, v6
	v_add_u32_e32 v93, v85, v7
	v_add_u32_e32 v94, v85, v8
	v_add_u32_e32 v95, v85, v9
	s_mov_b32 s3, s59
	s_cmpk_lg_i32 s92, 0x100
	s_cbranch_scc1 .Lsmp_map_keep115
	s_and_b32 s4, s6, 7
	s_lshr_b32 s5, s6, 3
	s_lshl_b32 s4, s4, 2
	s_lshr_b32 s2, s5, 3
	s_add_i32 s4, s4, s2
	s_and_b32 s5, s5, 7
	s_lshl_b32 s4, s4, 3
	s_or_b32 s6, s4, s5
	s_lshl_b32 s2, s6, 6
	s_lshl_b32 s3, s6, 3
